# P4b epilogue rewritten wide: permlane16 swaps, dwordx4 gate/T loads and MG stores, 8 row-items of loads in flight and the rest issued into retired accumulator registers
# speedup vs baseline: 1.0221x; 1.0048x over previous
; __device__ __forceinline__ float bflo(unsigned w) { return __uint_as_float(w << 16); }
; __device__ __forceinline__ float bfhi(unsigned w) { return __uint_as_float(w & 0xffff0000u); }
; __device__ __forceinline__ unsigned pk2(float lo, float hi) { f32x2 v = {lo, hi}; bf16x2_t b = __builtin_convertvector(v, bf16x2_t); return __builtin_bit_cast(unsigned, b); }
; __device__ __forceinline__ float sigm(float x) { return __builtin_amdgcn_rcpf(1.f + __expf(-x)); }
;     template <int QPR> __device__ __forceinline__ void tailq(int row, int c, const f32x4 v, int) const { quad(row, c, v); }
;     __device__ __forceinline__ void quad(int row, int c, const f32x4 a) const {
;         const u32x2 gw = *(const u32x2*)(Z + (size_t)row * NZ + ZC_MB + c);
;         const u32x2 tw = *(const u32x2*)(T + (size_t)row * D + c); const f32x4 t = {bflo(tw.x), bfhi(tw.x), bflo(tw.y), bfhi(tw.y)};
;         const float v0 = t[0] + a[0] * sigm(bflo(gw.x)), v1 = t[1] + a[1] * sigm(bfhi(gw.x)), v2 = t[2] + a[2] * sigm(bflo(gw.y)), v3 = t[3] + a[3] * sigm(bfhi(gw.y));
;         u32x2 w; w.x = pk2(v0, v1); w.y = pk2(v2, v3);
;         *(u32x2*)(MG + (size_t)row * D + c) = w; }
;     template <int QPR> __device__ __forceinline__ void tailq(int row, int c, const f32x4 v, int) const { quad(row, c, v); }
;     __device__ __forceinline__ void operator()(const f32x4 (&acc)[2][2][4][2], const pg8::Unit& u, int wr, int wc, int fr, int fq) const {
;         const int row0 = u.pm * 256 + wr * 64 + fr, col0 = u.pn * 256 + wc * 32 + 4 * fq;
; #pragma unroll
;         for (int ai = 0; ai < 2; ++ai)
; #pragma unroll
;             for (int m = 0; m < 4; ++m) { const int row = row0 + ai * 128 + m * 16;
; #pragma unroll
;                 for (int bj = 0; bj < 2; ++bj)
; #pragma unroll
;                     for (int n = 0; n < 2; ++n) { const int c = col0 + bj * 128 + n * 16;
;                         quad(row, c, acc[ai][bj][m][n]); } }
.LBB0_793:
	v_lshl_add_u32 v148, s85, 8, v160
	v_lshl_or_b32 v149, s84, 8, v162
	v_mov_b64_e32 v[152:153], s[46:47]
	v_mad_u64_u32 v[154:155], s[4:5], v148, s67, v[152:153]
	v_lshl_add_u64 v[154:155], v[154:155], 0, s[20:21]
	v_and_b32_e32 v151, 4, v162
	v_mul_u32_u24_e32 v151, 6, v151
	v_lshl_add_u32 v150, v149, 1, v151
	v_mov_b32_e32 v151, 0
	v_lshl_add_u64 v[154:155], v[154:155], 0, v[150:151]
	v_lshlrev_b32_e32 v152, 11, v148
	v_add_u32_e32 v152, v152, v150
	v_mov_b32_e32 v153, 0
	v_lshl_add_u64 v[156:157], s[42:43], 0, v[152:153]
	v_lshl_add_u64 v[158:159], s[48:49], 0, v[152:153]
	v_permlane16_swap_b32 v126, v122
	v_permlane16_swap_b32 v127, v123
	v_permlane16_swap_b32 v128, v124
	v_permlane16_swap_b32 v129, v125
	v_permlane16_swap_b32 v118, v114
	v_permlane16_swap_b32 v119, v115
	v_permlane16_swap_b32 v120, v116
	v_permlane16_swap_b32 v121, v117
	v_permlane16_swap_b32 v110, v106
	v_permlane16_swap_b32 v111, v107
	v_permlane16_swap_b32 v112, v108
	v_permlane16_swap_b32 v113, v109
	v_permlane16_swap_b32 v102, v98
	v_permlane16_swap_b32 v103, v99
	v_permlane16_swap_b32 v104, v100
	v_permlane16_swap_b32 v105, v101
	v_permlane16_swap_b32 v94, v90
	v_permlane16_swap_b32 v95, v91
	v_permlane16_swap_b32 v96, v92
	v_permlane16_swap_b32 v97, v93
	v_permlane16_swap_b32 v86, v82
	v_permlane16_swap_b32 v87, v83
	v_permlane16_swap_b32 v88, v84
	v_permlane16_swap_b32 v89, v85
	v_permlane16_swap_b32 v78, v74
	v_permlane16_swap_b32 v79, v75
	v_permlane16_swap_b32 v80, v76
	v_permlane16_swap_b32 v81, v77
	v_permlane16_swap_b32 v70, v66
	v_permlane16_swap_b32 v71, v67
	v_permlane16_swap_b32 v72, v68
	v_permlane16_swap_b32 v73, v69
	v_permlane16_swap_b32 v62, v58
	v_permlane16_swap_b32 v63, v59
	v_permlane16_swap_b32 v64, v60
	v_permlane16_swap_b32 v65, v61
	v_permlane16_swap_b32 v54, v50
	v_permlane16_swap_b32 v55, v51
	v_permlane16_swap_b32 v56, v52
	v_permlane16_swap_b32 v57, v53
	v_permlane16_swap_b32 v46, v42
	v_permlane16_swap_b32 v47, v43
	v_permlane16_swap_b32 v48, v44
	v_permlane16_swap_b32 v49, v45
	v_permlane16_swap_b32 v38, v34
	v_permlane16_swap_b32 v39, v35
	v_permlane16_swap_b32 v40, v36
	v_permlane16_swap_b32 v41, v37
	v_permlane16_swap_b32 v30, v26
	v_permlane16_swap_b32 v31, v27
	v_permlane16_swap_b32 v32, v28
	v_permlane16_swap_b32 v33, v29
	v_permlane16_swap_b32 v22, v18
	v_permlane16_swap_b32 v23, v19
	v_permlane16_swap_b32 v24, v20
	v_permlane16_swap_b32 v25, v21
	v_permlane16_swap_b32 v14, v10
	v_permlane16_swap_b32 v15, v11
	v_permlane16_swap_b32 v16, v12
	v_permlane16_swap_b32 v17, v13
	v_permlane16_swap_b32 v6, v2
	v_permlane16_swap_b32 v7, v3
	v_permlane16_swap_b32 v8, v4
	v_permlane16_swap_b32 v9, v5
	global_load_dwordx4 v[164:167], v[154:155], off
	global_load_dwordx4 v[168:171], v[156:157], off
	global_load_dwordx4 v[172:175], v[154:155], off offset:256
	global_load_dwordx4 v[176:179], v[156:157], off offset:256
	s_mov_b64 s[4:5], 0x3a000
	v_lshl_add_u64 v[154:155], v[154:155], 0, s[4:5]
	s_mov_b64 s[4:5], 0x8000
	v_lshl_add_u64 v[156:157], v[156:157], 0, s[4:5]
	global_load_dwordx4 v[180:183], v[154:155], off
	global_load_dwordx4 v[184:187], v[156:157], off
	global_load_dwordx4 v[204:207], v[154:155], off offset:256
	global_load_dwordx4 v[208:211], v[156:157], off offset:256
	s_mov_b64 s[4:5], 0x3a000
	v_lshl_add_u64 v[154:155], v[154:155], 0, s[4:5]
	s_mov_b64 s[4:5], 0x8000
	v_lshl_add_u64 v[156:157], v[156:157], 0, s[4:5]
	global_load_dwordx4 v[212:215], v[154:155], off
	global_load_dwordx4 v[216:219], v[156:157], off
	global_load_dwordx4 v[220:223], v[154:155], off offset:256
	global_load_dwordx4 v[224:227], v[156:157], off offset:256
	s_mov_b64 s[4:5], 0x3a000
	v_lshl_add_u64 v[154:155], v[154:155], 0, s[4:5]
	s_mov_b64 s[4:5], 0x8000
	v_lshl_add_u64 v[156:157], v[156:157], 0, s[4:5]
	global_load_dwordx4 v[228:231], v[154:155], off
	global_load_dwordx4 v[232:235], v[156:157], off
	global_load_dwordx4 v[236:239], v[154:155], off offset:256
	global_load_dwordx4 v[240:243], v[156:157], off offset:256
	s_mov_b64 s[4:5], 0x122000
	v_lshl_add_u64 v[154:155], v[154:155], 0, s[4:5]
	s_mov_b64 s[4:5], 0x28000
	v_lshl_add_u64 v[156:157], v[156:157], 0, s[4:5]
	s_waitcnt vmcnt(14)
	v_lshlrev_b32_e32 v148, 16, v164
	v_and_b32_e32 v149, 0xffff0000, v164
	v_lshlrev_b32_e32 v150, 16, v165
	v_and_b32_e32 v151, 0xffff0000, v165
	v_mul_f32_e32 v148, 0xbfb8aa3b, v148
	v_mul_f32_e32 v149, 0xbfb8aa3b, v149
	v_mul_f32_e32 v150, 0xbfb8aa3b, v150
	v_mul_f32_e32 v151, 0xbfb8aa3b, v151
	v_exp_f32_e32 v148, v148
	v_exp_f32_e32 v149, v149
	v_exp_f32_e32 v150, v150
	v_exp_f32_e32 v151, v151
	v_add_f32_e32 v148, 1.0, v148
	v_add_f32_e32 v149, 1.0, v149
	v_add_f32_e32 v150, 1.0, v150
	v_add_f32_e32 v151, 1.0, v151
	v_rcp_f32_e32 v148, v148
	v_rcp_f32_e32 v149, v149
	v_rcp_f32_e32 v150, v150
	v_rcp_f32_e32 v151, v151
	v_lshlrev_b32_e32 v164, 16, v168
	v_and_b32_e32 v165, 0xffff0000, v168
	v_lshlrev_b32_e32 v168, 16, v169
	v_and_b32_e32 v169, 0xffff0000, v169
	v_pk_fma_f32 v[126:127], v[126:127], v[148:149], v[164:165]
	v_pk_fma_f32 v[128:129], v[128:129], v[150:151], v[168:169]
	v_lshlrev_b32_e32 v148, 16, v166
	v_and_b32_e32 v149, 0xffff0000, v166
	v_lshlrev_b32_e32 v150, 16, v167
	v_and_b32_e32 v151, 0xffff0000, v167
	v_mul_f32_e32 v148, 0xbfb8aa3b, v148
	v_mul_f32_e32 v149, 0xbfb8aa3b, v149
	v_mul_f32_e32 v150, 0xbfb8aa3b, v150
	v_mul_f32_e32 v151, 0xbfb8aa3b, v151
	v_exp_f32_e32 v148, v148
	v_exp_f32_e32 v149, v149
	v_exp_f32_e32 v150, v150
	v_exp_f32_e32 v151, v151
	v_add_f32_e32 v148, 1.0, v148
	v_add_f32_e32 v149, 1.0, v149
	v_add_f32_e32 v150, 1.0, v150
	v_add_f32_e32 v151, 1.0, v151
	v_rcp_f32_e32 v148, v148
	v_rcp_f32_e32 v149, v149
	v_rcp_f32_e32 v150, v150
	v_rcp_f32_e32 v151, v151
	v_lshlrev_b32_e32 v166, 16, v170
	v_and_b32_e32 v167, 0xffff0000, v170
	v_lshlrev_b32_e32 v170, 16, v171
	v_and_b32_e32 v171, 0xffff0000, v171
	v_pk_fma_f32 v[122:123], v[122:123], v[148:149], v[166:167]
	v_pk_fma_f32 v[124:125], v[124:125], v[150:151], v[170:171]
	v_cvt_pk_bf16_f32 v164, v126, v127
	v_cvt_pk_bf16_f32 v165, v128, v129
	v_cvt_pk_bf16_f32 v166, v122, v123
	v_cvt_pk_bf16_f32 v167, v124, v125
	global_store_dwordx4 v[158:159], v[164:167], off
	global_load_dwordx4 v[126:129], v[154:155], off
	global_load_dwordx4 v[122:125], v[156:157], off
	s_waitcnt vmcnt(15)
; __device__ __forceinline__ float bflo(unsigned w) { return __uint_as_float(w << 16); }
; __device__ __forceinline__ float bfhi(unsigned w) { return __uint_as_float(w & 0xffff0000u); }
; __device__ __forceinline__ unsigned pk2(float lo, float hi) { f32x2 v = {lo, hi}; bf16x2_t b = __builtin_convertvector(v, bf16x2_t); return __builtin_bit_cast(unsigned, b); }
; __device__ __forceinline__ float sigm(float x) { return __builtin_amdgcn_rcpf(1.f + __expf(-x)); }
;     template <int QPR> __device__ __forceinline__ void tailq(int row, int c, const f32x4 v, int) const { quad(row, c, v); }
;     __device__ __forceinline__ void quad(int row, int c, const f32x4 a) const {
;         const u32x2 gw = *(const u32x2*)(Z + (size_t)row * NZ + ZC_MB + c);
;         const u32x2 tw = *(const u32x2*)(T + (size_t)row * D + c); const f32x4 t = {bflo(tw.x), bfhi(tw.x), bflo(tw.y), bfhi(tw.y)};
;         const float v0 = t[0] + a[0] * sigm(bflo(gw.x)), v1 = t[1] + a[1] * sigm(bfhi(gw.x)), v2 = t[2] + a[2] * sigm(bflo(gw.y)), v3 = t[3] + a[3] * sigm(bfhi(gw.y));
;         u32x2 w; w.x = pk2(v0, v1); w.y = pk2(v2, v3);
;         *(u32x2*)(MG + (size_t)row * D + c) = w; }
;     template <int QPR> __device__ __forceinline__ void tailq(int row, int c, const f32x4 v, int) const { quad(row, c, v); }
;     __device__ __forceinline__ void operator()(const f32x4 (&acc)[2][2][4][2], const pg8::Unit& u, int wr, int wc, int fr, int fq) const {
;         const int row0 = u.pm * 256 + wr * 64 + fr, col0 = u.pn * 256 + wc * 32 + 4 * fq;
; #pragma unroll
;         for (int ai = 0; ai < 2; ++ai)
; #pragma unroll
;             for (int m = 0; m < 4; ++m) { const int row = row0 + ai * 128 + m * 16;
; #pragma unroll
;                 for (int bj = 0; bj < 2; ++bj)
; #pragma unroll
;                     for (int n = 0; n < 2; ++n) { const int c = col0 + bj * 128 + n * 16;
;                         quad(row, c, acc[ai][bj][m][n]); } }
	v_lshlrev_b32_e32 v148, 16, v172
	v_and_b32_e32 v149, 0xffff0000, v172
	v_lshlrev_b32_e32 v150, 16, v173
	v_and_b32_e32 v151, 0xffff0000, v173
	v_mul_f32_e32 v148, 0xbfb8aa3b, v148
	v_mul_f32_e32 v149, 0xbfb8aa3b, v149
	v_mul_f32_e32 v150, 0xbfb8aa3b, v150
	v_mul_f32_e32 v151, 0xbfb8aa3b, v151
	v_exp_f32_e32 v148, v148
	v_exp_f32_e32 v149, v149
	v_exp_f32_e32 v150, v150
	v_exp_f32_e32 v151, v151
	v_add_f32_e32 v148, 1.0, v148
	v_add_f32_e32 v149, 1.0, v149
	v_add_f32_e32 v150, 1.0, v150
	v_add_f32_e32 v151, 1.0, v151
	v_rcp_f32_e32 v148, v148
	v_rcp_f32_e32 v149, v149
	v_rcp_f32_e32 v150, v150
	v_rcp_f32_e32 v151, v151
	v_lshlrev_b32_e32 v172, 16, v176
	v_and_b32_e32 v173, 0xffff0000, v176
	v_lshlrev_b32_e32 v176, 16, v177
	v_and_b32_e32 v177, 0xffff0000, v177
	v_pk_fma_f32 v[118:119], v[118:119], v[148:149], v[172:173]
	v_pk_fma_f32 v[120:121], v[120:121], v[150:151], v[176:177]
	v_lshlrev_b32_e32 v148, 16, v174
	v_and_b32_e32 v149, 0xffff0000, v174
	v_lshlrev_b32_e32 v150, 16, v175
	v_and_b32_e32 v151, 0xffff0000, v175
	v_mul_f32_e32 v148, 0xbfb8aa3b, v148
	v_mul_f32_e32 v149, 0xbfb8aa3b, v149
	v_mul_f32_e32 v150, 0xbfb8aa3b, v150
	v_mul_f32_e32 v151, 0xbfb8aa3b, v151
	v_exp_f32_e32 v148, v148
	v_exp_f32_e32 v149, v149
	v_exp_f32_e32 v150, v150
	v_exp_f32_e32 v151, v151
	v_add_f32_e32 v148, 1.0, v148
	v_add_f32_e32 v149, 1.0, v149
	v_add_f32_e32 v150, 1.0, v150
	v_add_f32_e32 v151, 1.0, v151
	v_rcp_f32_e32 v148, v148
	v_rcp_f32_e32 v149, v149
	v_rcp_f32_e32 v150, v150
	v_rcp_f32_e32 v151, v151
	v_lshlrev_b32_e32 v174, 16, v178
	v_and_b32_e32 v175, 0xffff0000, v178
	v_lshlrev_b32_e32 v178, 16, v179
	v_and_b32_e32 v179, 0xffff0000, v179
	v_pk_fma_f32 v[114:115], v[114:115], v[148:149], v[174:175]
	v_pk_fma_f32 v[116:117], v[116:117], v[150:151], v[178:179]
	v_cvt_pk_bf16_f32 v172, v118, v119
	v_cvt_pk_bf16_f32 v173, v120, v121
	v_cvt_pk_bf16_f32 v174, v114, v115
	v_cvt_pk_bf16_f32 v175, v116, v117
	global_store_dwordx4 v[158:159], v[172:175], off offset:256
	s_mov_b64 s[4:5], 0x8000
	v_lshl_add_u64 v[158:159], v[158:159], 0, s[4:5]
	global_load_dwordx4 v[118:121], v[154:155], off offset:256
	global_load_dwordx4 v[114:117], v[156:157], off offset:256
	s_mov_b64 s[4:5], 0x3a000
	v_lshl_add_u64 v[154:155], v[154:155], 0, s[4:5]
	s_mov_b64 s[4:5], 0x8000
	v_lshl_add_u64 v[156:157], v[156:157], 0, s[4:5]
	s_waitcnt vmcnt(16)
	v_lshlrev_b32_e32 v148, 16, v180
	v_and_b32_e32 v149, 0xffff0000, v180
	v_lshlrev_b32_e32 v150, 16, v181
	v_and_b32_e32 v151, 0xffff0000, v181
	v_mul_f32_e32 v148, 0xbfb8aa3b, v148
	v_mul_f32_e32 v149, 0xbfb8aa3b, v149
	v_mul_f32_e32 v150, 0xbfb8aa3b, v150
	v_mul_f32_e32 v151, 0xbfb8aa3b, v151
	v_exp_f32_e32 v148, v148
	v_exp_f32_e32 v149, v149
	v_exp_f32_e32 v150, v150
	v_exp_f32_e32 v151, v151
	v_add_f32_e32 v148, 1.0, v148
	v_add_f32_e32 v149, 1.0, v149
	v_add_f32_e32 v150, 1.0, v150
	v_add_f32_e32 v151, 1.0, v151
	v_rcp_f32_e32 v148, v148
	v_rcp_f32_e32 v149, v149
	v_rcp_f32_e32 v150, v150
	v_rcp_f32_e32 v151, v151
	v_lshlrev_b32_e32 v180, 16, v184
	v_and_b32_e32 v181, 0xffff0000, v184
	v_lshlrev_b32_e32 v184, 16, v185
	v_and_b32_e32 v185, 0xffff0000, v185
	v_pk_fma_f32 v[110:111], v[110:111], v[148:149], v[180:181]
	v_pk_fma_f32 v[112:113], v[112:113], v[150:151], v[184:185]
	v_lshlrev_b32_e32 v148, 16, v182
	v_and_b32_e32 v149, 0xffff0000, v182
	v_lshlrev_b32_e32 v150, 16, v183
	v_and_b32_e32 v151, 0xffff0000, v183
	v_mul_f32_e32 v148, 0xbfb8aa3b, v148
	v_mul_f32_e32 v149, 0xbfb8aa3b, v149
	v_mul_f32_e32 v150, 0xbfb8aa3b, v150
	v_mul_f32_e32 v151, 0xbfb8aa3b, v151
	v_exp_f32_e32 v148, v148
	v_exp_f32_e32 v149, v149
	v_exp_f32_e32 v150, v150
	v_exp_f32_e32 v151, v151
	v_add_f32_e32 v148, 1.0, v148
	v_add_f32_e32 v149, 1.0, v149
	v_add_f32_e32 v150, 1.0, v150
	v_add_f32_e32 v151, 1.0, v151
	v_rcp_f32_e32 v148, v148
	v_rcp_f32_e32 v149, v149
	v_rcp_f32_e32 v150, v150
	v_rcp_f32_e32 v151, v151
	v_lshlrev_b32_e32 v182, 16, v186
	v_and_b32_e32 v183, 0xffff0000, v186
	v_lshlrev_b32_e32 v186, 16, v187
	v_and_b32_e32 v187, 0xffff0000, v187
	v_pk_fma_f32 v[106:107], v[106:107], v[148:149], v[182:183]
	v_pk_fma_f32 v[108:109], v[108:109], v[150:151], v[186:187]
	v_cvt_pk_bf16_f32 v180, v110, v111
	v_cvt_pk_bf16_f32 v181, v112, v113
	v_cvt_pk_bf16_f32 v182, v106, v107
	v_cvt_pk_bf16_f32 v183, v108, v109
	global_store_dwordx4 v[158:159], v[180:183], off
	global_load_dwordx4 v[110:113], v[154:155], off
	global_load_dwordx4 v[106:109], v[156:157], off
	s_waitcnt vmcnt(17)
; __device__ __forceinline__ float bflo(unsigned w) { return __uint_as_float(w << 16); }
; __device__ __forceinline__ float bfhi(unsigned w) { return __uint_as_float(w & 0xffff0000u); }
; __device__ __forceinline__ unsigned pk2(float lo, float hi) { f32x2 v = {lo, hi}; bf16x2_t b = __builtin_convertvector(v, bf16x2_t); return __builtin_bit_cast(unsigned, b); }
; __device__ __forceinline__ float sigm(float x) { return __builtin_amdgcn_rcpf(1.f + __expf(-x)); }
;     template <int QPR> __device__ __forceinline__ void tailq(int row, int c, const f32x4 v, int) const { quad(row, c, v); }
;     __device__ __forceinline__ void quad(int row, int c, const f32x4 a) const {
;         const u32x2 gw = *(const u32x2*)(Z + (size_t)row * NZ + ZC_MB + c);
;         const u32x2 tw = *(const u32x2*)(T + (size_t)row * D + c); const f32x4 t = {bflo(tw.x), bfhi(tw.x), bflo(tw.y), bfhi(tw.y)};
;         const float v0 = t[0] + a[0] * sigm(bflo(gw.x)), v1 = t[1] + a[1] * sigm(bfhi(gw.x)), v2 = t[2] + a[2] * sigm(bflo(gw.y)), v3 = t[3] + a[3] * sigm(bfhi(gw.y));
;         u32x2 w; w.x = pk2(v0, v1); w.y = pk2(v2, v3);
;         *(u32x2*)(MG + (size_t)row * D + c) = w; }
;     template <int QPR> __device__ __forceinline__ void tailq(int row, int c, const f32x4 v, int) const { quad(row, c, v); }
;     __device__ __forceinline__ void operator()(const f32x4 (&acc)[2][2][4][2], const pg8::Unit& u, int wr, int wc, int fr, int fq) const {
;         const int row0 = u.pm * 256 + wr * 64 + fr, col0 = u.pn * 256 + wc * 32 + 4 * fq;
; #pragma unroll
;         for (int ai = 0; ai < 2; ++ai)
; #pragma unroll
;             for (int m = 0; m < 4; ++m) { const int row = row0 + ai * 128 + m * 16;
; #pragma unroll
;                 for (int bj = 0; bj < 2; ++bj)
; #pragma unroll
;                     for (int n = 0; n < 2; ++n) { const int c = col0 + bj * 128 + n * 16;
;                         quad(row, c, acc[ai][bj][m][n]); } }
	v_lshlrev_b32_e32 v148, 16, v204
	v_and_b32_e32 v149, 0xffff0000, v204
	v_lshlrev_b32_e32 v150, 16, v205
	v_and_b32_e32 v151, 0xffff0000, v205
	v_mul_f32_e32 v148, 0xbfb8aa3b, v148
	v_mul_f32_e32 v149, 0xbfb8aa3b, v149
	v_mul_f32_e32 v150, 0xbfb8aa3b, v150
	v_mul_f32_e32 v151, 0xbfb8aa3b, v151
	v_exp_f32_e32 v148, v148
	v_exp_f32_e32 v149, v149
	v_exp_f32_e32 v150, v150
	v_exp_f32_e32 v151, v151
	v_add_f32_e32 v148, 1.0, v148
	v_add_f32_e32 v149, 1.0, v149
	v_add_f32_e32 v150, 1.0, v150
	v_add_f32_e32 v151, 1.0, v151
	v_rcp_f32_e32 v148, v148
	v_rcp_f32_e32 v149, v149
	v_rcp_f32_e32 v150, v150
	v_rcp_f32_e32 v151, v151
	v_lshlrev_b32_e32 v204, 16, v208
	v_and_b32_e32 v205, 0xffff0000, v208
	v_lshlrev_b32_e32 v208, 16, v209
	v_and_b32_e32 v209, 0xffff0000, v209
	v_pk_fma_f32 v[102:103], v[102:103], v[148:149], v[204:205]
	v_pk_fma_f32 v[104:105], v[104:105], v[150:151], v[208:209]
	v_lshlrev_b32_e32 v148, 16, v206
	v_and_b32_e32 v149, 0xffff0000, v206
	v_lshlrev_b32_e32 v150, 16, v207
	v_and_b32_e32 v151, 0xffff0000, v207
	v_mul_f32_e32 v148, 0xbfb8aa3b, v148
	v_mul_f32_e32 v149, 0xbfb8aa3b, v149
	v_mul_f32_e32 v150, 0xbfb8aa3b, v150
	v_mul_f32_e32 v151, 0xbfb8aa3b, v151
	v_exp_f32_e32 v148, v148
	v_exp_f32_e32 v149, v149
	v_exp_f32_e32 v150, v150
	v_exp_f32_e32 v151, v151
	v_add_f32_e32 v148, 1.0, v148
	v_add_f32_e32 v149, 1.0, v149
	v_add_f32_e32 v150, 1.0, v150
	v_add_f32_e32 v151, 1.0, v151
	v_rcp_f32_e32 v148, v148
	v_rcp_f32_e32 v149, v149
	v_rcp_f32_e32 v150, v150
	v_rcp_f32_e32 v151, v151
	v_lshlrev_b32_e32 v206, 16, v210
	v_and_b32_e32 v207, 0xffff0000, v210
	v_lshlrev_b32_e32 v210, 16, v211
	v_and_b32_e32 v211, 0xffff0000, v211
	v_pk_fma_f32 v[98:99], v[98:99], v[148:149], v[206:207]
	v_pk_fma_f32 v[100:101], v[100:101], v[150:151], v[210:211]
	v_cvt_pk_bf16_f32 v204, v102, v103
	v_cvt_pk_bf16_f32 v205, v104, v105
	v_cvt_pk_bf16_f32 v206, v98, v99
	v_cvt_pk_bf16_f32 v207, v100, v101
	global_store_dwordx4 v[158:159], v[204:207], off offset:256
	s_mov_b64 s[4:5], 0x8000
	v_lshl_add_u64 v[158:159], v[158:159], 0, s[4:5]
	global_load_dwordx4 v[102:105], v[154:155], off offset:256
	global_load_dwordx4 v[98:101], v[156:157], off offset:256
	s_mov_b64 s[4:5], 0x3a000
	v_lshl_add_u64 v[154:155], v[154:155], 0, s[4:5]
	s_mov_b64 s[4:5], 0x8000
	v_lshl_add_u64 v[156:157], v[156:157], 0, s[4:5]
	s_waitcnt vmcnt(18)
	v_lshlrev_b32_e32 v148, 16, v212
	v_and_b32_e32 v149, 0xffff0000, v212
	v_lshlrev_b32_e32 v150, 16, v213
	v_and_b32_e32 v151, 0xffff0000, v213
	v_mul_f32_e32 v148, 0xbfb8aa3b, v148
	v_mul_f32_e32 v149, 0xbfb8aa3b, v149
	v_mul_f32_e32 v150, 0xbfb8aa3b, v150
	v_mul_f32_e32 v151, 0xbfb8aa3b, v151
	v_exp_f32_e32 v148, v148
	v_exp_f32_e32 v149, v149
	v_exp_f32_e32 v150, v150
	v_exp_f32_e32 v151, v151
	v_add_f32_e32 v148, 1.0, v148
	v_add_f32_e32 v149, 1.0, v149
	v_add_f32_e32 v150, 1.0, v150
	v_add_f32_e32 v151, 1.0, v151
	v_rcp_f32_e32 v148, v148
	v_rcp_f32_e32 v149, v149
	v_rcp_f32_e32 v150, v150
	v_rcp_f32_e32 v151, v151
	v_lshlrev_b32_e32 v212, 16, v216
	v_and_b32_e32 v213, 0xffff0000, v216
	v_lshlrev_b32_e32 v216, 16, v217
	v_and_b32_e32 v217, 0xffff0000, v217
	v_pk_fma_f32 v[94:95], v[94:95], v[148:149], v[212:213]
	v_pk_fma_f32 v[96:97], v[96:97], v[150:151], v[216:217]
	v_lshlrev_b32_e32 v148, 16, v214
	v_and_b32_e32 v149, 0xffff0000, v214
	v_lshlrev_b32_e32 v150, 16, v215
	v_and_b32_e32 v151, 0xffff0000, v215
	v_mul_f32_e32 v148, 0xbfb8aa3b, v148
	v_mul_f32_e32 v149, 0xbfb8aa3b, v149
	v_mul_f32_e32 v150, 0xbfb8aa3b, v150
	v_mul_f32_e32 v151, 0xbfb8aa3b, v151
	v_exp_f32_e32 v148, v148
	v_exp_f32_e32 v149, v149
	v_exp_f32_e32 v150, v150
	v_exp_f32_e32 v151, v151
	v_add_f32_e32 v148, 1.0, v148
	v_add_f32_e32 v149, 1.0, v149
	v_add_f32_e32 v150, 1.0, v150
	v_add_f32_e32 v151, 1.0, v151
	v_rcp_f32_e32 v148, v148
	v_rcp_f32_e32 v149, v149
	v_rcp_f32_e32 v150, v150
	v_rcp_f32_e32 v151, v151
	v_lshlrev_b32_e32 v214, 16, v218
	v_and_b32_e32 v215, 0xffff0000, v218
	v_lshlrev_b32_e32 v218, 16, v219
	v_and_b32_e32 v219, 0xffff0000, v219
	v_pk_fma_f32 v[90:91], v[90:91], v[148:149], v[214:215]
	v_pk_fma_f32 v[92:93], v[92:93], v[150:151], v[218:219]
	v_cvt_pk_bf16_f32 v212, v94, v95
	v_cvt_pk_bf16_f32 v213, v96, v97
	v_cvt_pk_bf16_f32 v214, v90, v91
	v_cvt_pk_bf16_f32 v215, v92, v93
	global_store_dwordx4 v[158:159], v[212:215], off
	global_load_dwordx4 v[94:97], v[154:155], off
	global_load_dwordx4 v[90:93], v[156:157], off
	s_waitcnt vmcnt(19)
	v_lshlrev_b32_e32 v148, 16, v220
	v_and_b32_e32 v149, 0xffff0000, v220
	v_lshlrev_b32_e32 v150, 16, v221
	v_and_b32_e32 v151, 0xffff0000, v221
	v_mul_f32_e32 v148, 0xbfb8aa3b, v148
	v_mul_f32_e32 v149, 0xbfb8aa3b, v149
	v_mul_f32_e32 v150, 0xbfb8aa3b, v150
	v_mul_f32_e32 v151, 0xbfb8aa3b, v151
	v_exp_f32_e32 v148, v148
	v_exp_f32_e32 v149, v149
	v_exp_f32_e32 v150, v150
	v_exp_f32_e32 v151, v151
	v_add_f32_e32 v148, 1.0, v148
	v_add_f32_e32 v149, 1.0, v149
	v_add_f32_e32 v150, 1.0, v150
	v_add_f32_e32 v151, 1.0, v151
	v_rcp_f32_e32 v148, v148
	v_rcp_f32_e32 v149, v149
	v_rcp_f32_e32 v150, v150
	v_rcp_f32_e32 v151, v151
	v_lshlrev_b32_e32 v220, 16, v224
	v_and_b32_e32 v221, 0xffff0000, v224
	v_lshlrev_b32_e32 v224, 16, v225
	v_and_b32_e32 v225, 0xffff0000, v225
	v_pk_fma_f32 v[86:87], v[86:87], v[148:149], v[220:221]
	v_pk_fma_f32 v[88:89], v[88:89], v[150:151], v[224:225]
	v_lshlrev_b32_e32 v148, 16, v222
	v_and_b32_e32 v149, 0xffff0000, v222
	v_lshlrev_b32_e32 v150, 16, v223
	v_and_b32_e32 v151, 0xffff0000, v223
	v_mul_f32_e32 v148, 0xbfb8aa3b, v148
	v_mul_f32_e32 v149, 0xbfb8aa3b, v149
	v_mul_f32_e32 v150, 0xbfb8aa3b, v150
	v_mul_f32_e32 v151, 0xbfb8aa3b, v151
	v_exp_f32_e32 v148, v148
	v_exp_f32_e32 v149, v149
	v_exp_f32_e32 v150, v150
	v_exp_f32_e32 v151, v151
	v_add_f32_e32 v148, 1.0, v148
	v_add_f32_e32 v149, 1.0, v149
	v_add_f32_e32 v150, 1.0, v150
	v_add_f32_e32 v151, 1.0, v151
	v_rcp_f32_e32 v148, v148
	v_rcp_f32_e32 v149, v149
	v_rcp_f32_e32 v150, v150
	v_rcp_f32_e32 v151, v151
	v_lshlrev_b32_e32 v222, 16, v226
	v_and_b32_e32 v223, 0xffff0000, v226
	v_lshlrev_b32_e32 v226, 16, v227
	v_and_b32_e32 v227, 0xffff0000, v227
	v_pk_fma_f32 v[82:83], v[82:83], v[148:149], v[222:223]
	v_pk_fma_f32 v[84:85], v[84:85], v[150:151], v[226:227]
	v_cvt_pk_bf16_f32 v220, v86, v87
	v_cvt_pk_bf16_f32 v221, v88, v89
	v_cvt_pk_bf16_f32 v222, v82, v83
	v_cvt_pk_bf16_f32 v223, v84, v85
	global_store_dwordx4 v[158:159], v[220:223], off offset:256
	s_mov_b64 s[4:5], 0x8000
	v_lshl_add_u64 v[158:159], v[158:159], 0, s[4:5]
	global_load_dwordx4 v[86:89], v[154:155], off offset:256
	global_load_dwordx4 v[82:85], v[156:157], off offset:256
	s_mov_b64 s[4:5], 0x3a000
	v_lshl_add_u64 v[154:155], v[154:155], 0, s[4:5]
	s_mov_b64 s[4:5], 0x8000
	v_lshl_add_u64 v[156:157], v[156:157], 0, s[4:5]
	s_waitcnt vmcnt(20)
; __device__ __forceinline__ float bflo(unsigned w) { return __uint_as_float(w << 16); }
; __device__ __forceinline__ float bfhi(unsigned w) { return __uint_as_float(w & 0xffff0000u); }
; __device__ __forceinline__ unsigned pk2(float lo, float hi) { f32x2 v = {lo, hi}; bf16x2_t b = __builtin_convertvector(v, bf16x2_t); return __builtin_bit_cast(unsigned, b); }
;     template <int QPR> __device__ __forceinline__ void tailq(int row, int c, const f32x4 v, int) const { quad(row, c, v); }
; __device__ __forceinline__ float sigm(float x) { return __builtin_amdgcn_rcpf(1.f + __expf(-x)); }
;     __device__ __forceinline__ void quad(int row, int c, const f32x4 a) const {
;         const u32x2 gw = *(const u32x2*)(Z + (size_t)row * NZ + ZC_MB + c);
;         const u32x2 tw = *(const u32x2*)(T + (size_t)row * D + c); const f32x4 t = {bflo(tw.x), bfhi(tw.x), bflo(tw.y), bfhi(tw.y)};
;         const float v0 = t[0] + a[0] * sigm(bflo(gw.x)), v1 = t[1] + a[1] * sigm(bfhi(gw.x)), v2 = t[2] + a[2] * sigm(bflo(gw.y)), v3 = t[3] + a[3] * sigm(bfhi(gw.y));
;         u32x2 w; w.x = pk2(v0, v1); w.y = pk2(v2, v3);
;         *(u32x2*)(MG + (size_t)row * D + c) = w; }
;     template <int QPR> __device__ __forceinline__ void tailq(int row, int c, const f32x4 v, int) const { quad(row, c, v); }
;     __device__ __forceinline__ void operator()(const f32x4 (&acc)[2][2][4][2], const pg8::Unit& u, int wr, int wc, int fr, int fq) const {
;         const int row0 = u.pm * 256 + wr * 64 + fr, col0 = u.pn * 256 + wc * 32 + 4 * fq;
; #pragma unroll
;         for (int ai = 0; ai < 2; ++ai)
; #pragma unroll
;             for (int m = 0; m < 4; ++m) { const int row = row0 + ai * 128 + m * 16;
; #pragma unroll
;                 for (int bj = 0; bj < 2; ++bj)
; #pragma unroll
;                     for (int n = 0; n < 2; ++n) { const int c = col0 + bj * 128 + n * 16;
;                         quad(row, c, acc[ai][bj][m][n]); } }
	v_lshlrev_b32_e32 v148, 16, v228
	v_and_b32_e32 v149, 0xffff0000, v228
	v_lshlrev_b32_e32 v150, 16, v229
	v_and_b32_e32 v151, 0xffff0000, v229
	v_mul_f32_e32 v148, 0xbfb8aa3b, v148
	v_mul_f32_e32 v149, 0xbfb8aa3b, v149
	v_mul_f32_e32 v150, 0xbfb8aa3b, v150
	v_mul_f32_e32 v151, 0xbfb8aa3b, v151
	v_exp_f32_e32 v148, v148
	v_exp_f32_e32 v149, v149
	v_exp_f32_e32 v150, v150
	v_exp_f32_e32 v151, v151
	v_add_f32_e32 v148, 1.0, v148
	v_add_f32_e32 v149, 1.0, v149
	v_add_f32_e32 v150, 1.0, v150
	v_add_f32_e32 v151, 1.0, v151
	v_rcp_f32_e32 v148, v148
	v_rcp_f32_e32 v149, v149
	v_rcp_f32_e32 v150, v150
	v_rcp_f32_e32 v151, v151
	v_lshlrev_b32_e32 v228, 16, v232
	v_and_b32_e32 v229, 0xffff0000, v232
	v_lshlrev_b32_e32 v232, 16, v233
	v_and_b32_e32 v233, 0xffff0000, v233
	v_pk_fma_f32 v[78:79], v[78:79], v[148:149], v[228:229]
	v_pk_fma_f32 v[80:81], v[80:81], v[150:151], v[232:233]
	v_lshlrev_b32_e32 v148, 16, v230
	v_and_b32_e32 v149, 0xffff0000, v230
	v_lshlrev_b32_e32 v150, 16, v231
	v_and_b32_e32 v151, 0xffff0000, v231
	v_mul_f32_e32 v148, 0xbfb8aa3b, v148
	v_mul_f32_e32 v149, 0xbfb8aa3b, v149
	v_mul_f32_e32 v150, 0xbfb8aa3b, v150
	v_mul_f32_e32 v151, 0xbfb8aa3b, v151
	v_exp_f32_e32 v148, v148
	v_exp_f32_e32 v149, v149
	v_exp_f32_e32 v150, v150
	v_exp_f32_e32 v151, v151
	v_add_f32_e32 v148, 1.0, v148
	v_add_f32_e32 v149, 1.0, v149
	v_add_f32_e32 v150, 1.0, v150
	v_add_f32_e32 v151, 1.0, v151
	v_rcp_f32_e32 v148, v148
	v_rcp_f32_e32 v149, v149
	v_rcp_f32_e32 v150, v150
	v_rcp_f32_e32 v151, v151
	v_lshlrev_b32_e32 v230, 16, v234
	v_and_b32_e32 v231, 0xffff0000, v234
	v_lshlrev_b32_e32 v234, 16, v235
	v_and_b32_e32 v235, 0xffff0000, v235
	v_pk_fma_f32 v[74:75], v[74:75], v[148:149], v[230:231]
	v_pk_fma_f32 v[76:77], v[76:77], v[150:151], v[234:235]
	v_cvt_pk_bf16_f32 v228, v78, v79
	v_cvt_pk_bf16_f32 v229, v80, v81
	v_cvt_pk_bf16_f32 v230, v74, v75
	v_cvt_pk_bf16_f32 v231, v76, v77
	global_store_dwordx4 v[158:159], v[228:231], off
	global_load_dwordx4 v[78:81], v[154:155], off
	global_load_dwordx4 v[74:77], v[156:157], off
	s_waitcnt vmcnt(21)
	v_lshlrev_b32_e32 v148, 16, v236
	v_and_b32_e32 v149, 0xffff0000, v236
	v_lshlrev_b32_e32 v150, 16, v237
	v_and_b32_e32 v151, 0xffff0000, v237
	v_mul_f32_e32 v148, 0xbfb8aa3b, v148
	v_mul_f32_e32 v149, 0xbfb8aa3b, v149
	v_mul_f32_e32 v150, 0xbfb8aa3b, v150
	v_mul_f32_e32 v151, 0xbfb8aa3b, v151
	v_exp_f32_e32 v148, v148
	v_exp_f32_e32 v149, v149
	v_exp_f32_e32 v150, v150
	v_exp_f32_e32 v151, v151
	v_add_f32_e32 v148, 1.0, v148
	v_add_f32_e32 v149, 1.0, v149
	v_add_f32_e32 v150, 1.0, v150
	v_add_f32_e32 v151, 1.0, v151
	v_rcp_f32_e32 v148, v148
	v_rcp_f32_e32 v149, v149
	v_rcp_f32_e32 v150, v150
	v_rcp_f32_e32 v151, v151
	v_lshlrev_b32_e32 v236, 16, v240
	v_and_b32_e32 v237, 0xffff0000, v240
	v_lshlrev_b32_e32 v240, 16, v241
	v_and_b32_e32 v241, 0xffff0000, v241
	v_pk_fma_f32 v[70:71], v[70:71], v[148:149], v[236:237]
	v_pk_fma_f32 v[72:73], v[72:73], v[150:151], v[240:241]
	v_lshlrev_b32_e32 v148, 16, v238
	v_and_b32_e32 v149, 0xffff0000, v238
	v_lshlrev_b32_e32 v150, 16, v239
	v_and_b32_e32 v151, 0xffff0000, v239
	v_mul_f32_e32 v148, 0xbfb8aa3b, v148
	v_mul_f32_e32 v149, 0xbfb8aa3b, v149
	v_mul_f32_e32 v150, 0xbfb8aa3b, v150
	v_mul_f32_e32 v151, 0xbfb8aa3b, v151
	v_exp_f32_e32 v148, v148
	v_exp_f32_e32 v149, v149
	v_exp_f32_e32 v150, v150
	v_exp_f32_e32 v151, v151
	v_add_f32_e32 v148, 1.0, v148
	v_add_f32_e32 v149, 1.0, v149
	v_add_f32_e32 v150, 1.0, v150
	v_add_f32_e32 v151, 1.0, v151
	v_rcp_f32_e32 v148, v148
	v_rcp_f32_e32 v149, v149
	v_rcp_f32_e32 v150, v150
	v_rcp_f32_e32 v151, v151
	v_lshlrev_b32_e32 v238, 16, v242
	v_and_b32_e32 v239, 0xffff0000, v242
	v_lshlrev_b32_e32 v242, 16, v243
	v_and_b32_e32 v243, 0xffff0000, v243
	v_pk_fma_f32 v[66:67], v[66:67], v[148:149], v[238:239]
	v_pk_fma_f32 v[68:69], v[68:69], v[150:151], v[242:243]
	v_cvt_pk_bf16_f32 v236, v70, v71
	v_cvt_pk_bf16_f32 v237, v72, v73
	v_cvt_pk_bf16_f32 v238, v66, v67
	v_cvt_pk_bf16_f32 v239, v68, v69
	global_store_dwordx4 v[158:159], v[236:239], off offset:256
	s_mov_b64 s[4:5], 0x28000
	v_lshl_add_u64 v[158:159], v[158:159], 0, s[4:5]
	global_load_dwordx4 v[70:73], v[154:155], off offset:256
	global_load_dwordx4 v[66:69], v[156:157], off offset:256
	s_waitcnt vmcnt(21)
	v_lshlrev_b32_e32 v148, 16, v126
	v_and_b32_e32 v149, 0xffff0000, v126
	v_lshlrev_b32_e32 v150, 16, v127
	v_and_b32_e32 v151, 0xffff0000, v127
	v_mul_f32_e32 v148, 0xbfb8aa3b, v148
	v_mul_f32_e32 v149, 0xbfb8aa3b, v149
	v_mul_f32_e32 v150, 0xbfb8aa3b, v150
	v_mul_f32_e32 v151, 0xbfb8aa3b, v151
	v_exp_f32_e32 v148, v148
	v_exp_f32_e32 v149, v149
	v_exp_f32_e32 v150, v150
	v_exp_f32_e32 v151, v151
	v_add_f32_e32 v148, 1.0, v148
	v_add_f32_e32 v149, 1.0, v149
	v_add_f32_e32 v150, 1.0, v150
	v_add_f32_e32 v151, 1.0, v151
	v_rcp_f32_e32 v148, v148
	v_rcp_f32_e32 v149, v149
	v_rcp_f32_e32 v150, v150
	v_rcp_f32_e32 v151, v151
	v_lshlrev_b32_e32 v126, 16, v122
	v_and_b32_e32 v127, 0xffff0000, v122
	v_lshlrev_b32_e32 v122, 16, v123
	v_and_b32_e32 v123, 0xffff0000, v123
	v_pk_fma_f32 v[62:63], v[62:63], v[148:149], v[126:127]
	v_pk_fma_f32 v[64:65], v[64:65], v[150:151], v[122:123]
	v_lshlrev_b32_e32 v148, 16, v128
	v_and_b32_e32 v149, 0xffff0000, v128
	v_lshlrev_b32_e32 v150, 16, v129
	v_and_b32_e32 v151, 0xffff0000, v129
	v_mul_f32_e32 v148, 0xbfb8aa3b, v148
	v_mul_f32_e32 v149, 0xbfb8aa3b, v149
	v_mul_f32_e32 v150, 0xbfb8aa3b, v150
	v_mul_f32_e32 v151, 0xbfb8aa3b, v151
	v_exp_f32_e32 v148, v148
	v_exp_f32_e32 v149, v149
	v_exp_f32_e32 v150, v150
	v_exp_f32_e32 v151, v151
	v_add_f32_e32 v148, 1.0, v148
	v_add_f32_e32 v149, 1.0, v149
	v_add_f32_e32 v150, 1.0, v150
	v_add_f32_e32 v151, 1.0, v151
	v_rcp_f32_e32 v148, v148
	v_rcp_f32_e32 v149, v149
	v_rcp_f32_e32 v150, v150
	v_rcp_f32_e32 v151, v151
	v_lshlrev_b32_e32 v128, 16, v124
	v_and_b32_e32 v129, 0xffff0000, v124
	v_lshlrev_b32_e32 v124, 16, v125
	v_and_b32_e32 v125, 0xffff0000, v125
	v_pk_fma_f32 v[58:59], v[58:59], v[148:149], v[128:129]
	v_pk_fma_f32 v[60:61], v[60:61], v[150:151], v[124:125]
	v_cvt_pk_bf16_f32 v126, v62, v63
	v_cvt_pk_bf16_f32 v127, v64, v65
	v_cvt_pk_bf16_f32 v128, v58, v59
	v_cvt_pk_bf16_f32 v129, v60, v61
	global_store_dwordx4 v[158:159], v[126:129], off
	s_waitcnt vmcnt(19)
; __device__ __forceinline__ float bflo(unsigned w) { return __uint_as_float(w << 16); }
; __device__ __forceinline__ float bfhi(unsigned w) { return __uint_as_float(w & 0xffff0000u); }
; __device__ __forceinline__ unsigned pk2(float lo, float hi) { f32x2 v = {lo, hi}; bf16x2_t b = __builtin_convertvector(v, bf16x2_t); return __builtin_bit_cast(unsigned, b); }
;     template <int QPR> __device__ __forceinline__ void tailq(int row, int c, const f32x4 v, int) const { quad(row, c, v); }
; __device__ __forceinline__ float sigm(float x) { return __builtin_amdgcn_rcpf(1.f + __expf(-x)); }
;     __device__ __forceinline__ void quad(int row, int c, const f32x4 a) const {
;         const u32x2 gw = *(const u32x2*)(Z + (size_t)row * NZ + ZC_MB + c);
;         const u32x2 tw = *(const u32x2*)(T + (size_t)row * D + c); const f32x4 t = {bflo(tw.x), bfhi(tw.x), bflo(tw.y), bfhi(tw.y)};
;         const float v0 = t[0] + a[0] * sigm(bflo(gw.x)), v1 = t[1] + a[1] * sigm(bfhi(gw.x)), v2 = t[2] + a[2] * sigm(bflo(gw.y)), v3 = t[3] + a[3] * sigm(bfhi(gw.y));
;         u32x2 w; w.x = pk2(v0, v1); w.y = pk2(v2, v3);
;         *(u32x2*)(MG + (size_t)row * D + c) = w; }
;     template <int QPR> __device__ __forceinline__ void tailq(int row, int c, const f32x4 v, int) const { quad(row, c, v); }
;     __device__ __forceinline__ void operator()(const f32x4 (&acc)[2][2][4][2], const pg8::Unit& u, int wr, int wc, int fr, int fq) const {
;         const int row0 = u.pm * 256 + wr * 64 + fr, col0 = u.pn * 256 + wc * 32 + 4 * fq;
; #pragma unroll
;         for (int ai = 0; ai < 2; ++ai)
; #pragma unroll
;             for (int m = 0; m < 4; ++m) { const int row = row0 + ai * 128 + m * 16;
; #pragma unroll
;                 for (int bj = 0; bj < 2; ++bj)
; #pragma unroll
;                     for (int n = 0; n < 2; ++n) { const int c = col0 + bj * 128 + n * 16;
;                         quad(row, c, acc[ai][bj][m][n]); } }
	v_lshlrev_b32_e32 v148, 16, v118
	v_and_b32_e32 v149, 0xffff0000, v118
	v_lshlrev_b32_e32 v150, 16, v119
	v_and_b32_e32 v151, 0xffff0000, v119
	v_mul_f32_e32 v148, 0xbfb8aa3b, v148
	v_mul_f32_e32 v149, 0xbfb8aa3b, v149
	v_mul_f32_e32 v150, 0xbfb8aa3b, v150
	v_mul_f32_e32 v151, 0xbfb8aa3b, v151
	v_exp_f32_e32 v148, v148
	v_exp_f32_e32 v149, v149
	v_exp_f32_e32 v150, v150
	v_exp_f32_e32 v151, v151
	v_add_f32_e32 v148, 1.0, v148
	v_add_f32_e32 v149, 1.0, v149
	v_add_f32_e32 v150, 1.0, v150
	v_add_f32_e32 v151, 1.0, v151
	v_rcp_f32_e32 v148, v148
	v_rcp_f32_e32 v149, v149
	v_rcp_f32_e32 v150, v150
	v_rcp_f32_e32 v151, v151
	v_lshlrev_b32_e32 v118, 16, v114
	v_and_b32_e32 v119, 0xffff0000, v114
	v_lshlrev_b32_e32 v114, 16, v115
	v_and_b32_e32 v115, 0xffff0000, v115
	v_pk_fma_f32 v[54:55], v[54:55], v[148:149], v[118:119]
	v_pk_fma_f32 v[56:57], v[56:57], v[150:151], v[114:115]
	v_lshlrev_b32_e32 v148, 16, v120
	v_and_b32_e32 v149, 0xffff0000, v120
	v_lshlrev_b32_e32 v150, 16, v121
	v_and_b32_e32 v151, 0xffff0000, v121
	v_mul_f32_e32 v148, 0xbfb8aa3b, v148
	v_mul_f32_e32 v149, 0xbfb8aa3b, v149
	v_mul_f32_e32 v150, 0xbfb8aa3b, v150
	v_mul_f32_e32 v151, 0xbfb8aa3b, v151
	v_exp_f32_e32 v148, v148
	v_exp_f32_e32 v149, v149
	v_exp_f32_e32 v150, v150
	v_exp_f32_e32 v151, v151
	v_add_f32_e32 v148, 1.0, v148
	v_add_f32_e32 v149, 1.0, v149
	v_add_f32_e32 v150, 1.0, v150
	v_add_f32_e32 v151, 1.0, v151
	v_rcp_f32_e32 v148, v148
	v_rcp_f32_e32 v149, v149
	v_rcp_f32_e32 v150, v150
	v_rcp_f32_e32 v151, v151
	v_lshlrev_b32_e32 v120, 16, v116
	v_and_b32_e32 v121, 0xffff0000, v116
	v_lshlrev_b32_e32 v116, 16, v117
	v_and_b32_e32 v117, 0xffff0000, v117
	v_pk_fma_f32 v[50:51], v[50:51], v[148:149], v[120:121]
	v_pk_fma_f32 v[52:53], v[52:53], v[150:151], v[116:117]
	v_cvt_pk_bf16_f32 v118, v54, v55
	v_cvt_pk_bf16_f32 v119, v56, v57
	v_cvt_pk_bf16_f32 v120, v50, v51
	v_cvt_pk_bf16_f32 v121, v52, v53
	global_store_dwordx4 v[158:159], v[118:121], off offset:256
	s_mov_b64 s[4:5], 0x8000
	v_lshl_add_u64 v[158:159], v[158:159], 0, s[4:5]
	s_waitcnt vmcnt(17)
	v_lshlrev_b32_e32 v148, 16, v110
	v_and_b32_e32 v149, 0xffff0000, v110
	v_lshlrev_b32_e32 v150, 16, v111
	v_and_b32_e32 v151, 0xffff0000, v111
	v_mul_f32_e32 v148, 0xbfb8aa3b, v148
	v_mul_f32_e32 v149, 0xbfb8aa3b, v149
	v_mul_f32_e32 v150, 0xbfb8aa3b, v150
	v_mul_f32_e32 v151, 0xbfb8aa3b, v151
	v_exp_f32_e32 v148, v148
	v_exp_f32_e32 v149, v149
	v_exp_f32_e32 v150, v150
	v_exp_f32_e32 v151, v151
	v_add_f32_e32 v148, 1.0, v148
	v_add_f32_e32 v149, 1.0, v149
	v_add_f32_e32 v150, 1.0, v150
	v_add_f32_e32 v151, 1.0, v151
	v_rcp_f32_e32 v148, v148
	v_rcp_f32_e32 v149, v149
	v_rcp_f32_e32 v150, v150
	v_rcp_f32_e32 v151, v151
	v_lshlrev_b32_e32 v110, 16, v106
	v_and_b32_e32 v111, 0xffff0000, v106
	v_lshlrev_b32_e32 v106, 16, v107
	v_and_b32_e32 v107, 0xffff0000, v107
	v_pk_fma_f32 v[46:47], v[46:47], v[148:149], v[110:111]
	v_pk_fma_f32 v[48:49], v[48:49], v[150:151], v[106:107]
	v_lshlrev_b32_e32 v148, 16, v112
	v_and_b32_e32 v149, 0xffff0000, v112
	v_lshlrev_b32_e32 v150, 16, v113
	v_and_b32_e32 v151, 0xffff0000, v113
	v_mul_f32_e32 v148, 0xbfb8aa3b, v148
	v_mul_f32_e32 v149, 0xbfb8aa3b, v149
	v_mul_f32_e32 v150, 0xbfb8aa3b, v150
	v_mul_f32_e32 v151, 0xbfb8aa3b, v151
	v_exp_f32_e32 v148, v148
	v_exp_f32_e32 v149, v149
	v_exp_f32_e32 v150, v150
	v_exp_f32_e32 v151, v151
	v_add_f32_e32 v148, 1.0, v148
	v_add_f32_e32 v149, 1.0, v149
	v_add_f32_e32 v150, 1.0, v150
	v_add_f32_e32 v151, 1.0, v151
	v_rcp_f32_e32 v148, v148
	v_rcp_f32_e32 v149, v149
	v_rcp_f32_e32 v150, v150
	v_rcp_f32_e32 v151, v151
	v_lshlrev_b32_e32 v112, 16, v108
	v_and_b32_e32 v113, 0xffff0000, v108
	v_lshlrev_b32_e32 v108, 16, v109
	v_and_b32_e32 v109, 0xffff0000, v109
	v_pk_fma_f32 v[42:43], v[42:43], v[148:149], v[112:113]
	v_pk_fma_f32 v[44:45], v[44:45], v[150:151], v[108:109]
	v_cvt_pk_bf16_f32 v110, v46, v47
	v_cvt_pk_bf16_f32 v111, v48, v49
	v_cvt_pk_bf16_f32 v112, v42, v43
	v_cvt_pk_bf16_f32 v113, v44, v45
	global_store_dwordx4 v[158:159], v[110:113], off
	s_waitcnt vmcnt(15)
	v_lshlrev_b32_e32 v148, 16, v102
	v_and_b32_e32 v149, 0xffff0000, v102
	v_lshlrev_b32_e32 v150, 16, v103
	v_and_b32_e32 v151, 0xffff0000, v103
	v_mul_f32_e32 v148, 0xbfb8aa3b, v148
	v_mul_f32_e32 v149, 0xbfb8aa3b, v149
	v_mul_f32_e32 v150, 0xbfb8aa3b, v150
	v_mul_f32_e32 v151, 0xbfb8aa3b, v151
	v_exp_f32_e32 v148, v148
	v_exp_f32_e32 v149, v149
	v_exp_f32_e32 v150, v150
	v_exp_f32_e32 v151, v151
	v_add_f32_e32 v148, 1.0, v148
	v_add_f32_e32 v149, 1.0, v149
	v_add_f32_e32 v150, 1.0, v150
	v_add_f32_e32 v151, 1.0, v151
	v_rcp_f32_e32 v148, v148
	v_rcp_f32_e32 v149, v149
	v_rcp_f32_e32 v150, v150
	v_rcp_f32_e32 v151, v151
	v_lshlrev_b32_e32 v102, 16, v98
	v_and_b32_e32 v103, 0xffff0000, v98
	v_lshlrev_b32_e32 v98, 16, v99
	v_and_b32_e32 v99, 0xffff0000, v99
	v_pk_fma_f32 v[38:39], v[38:39], v[148:149], v[102:103]
	v_pk_fma_f32 v[40:41], v[40:41], v[150:151], v[98:99]
	v_lshlrev_b32_e32 v148, 16, v104
	v_and_b32_e32 v149, 0xffff0000, v104
	v_lshlrev_b32_e32 v150, 16, v105
	v_and_b32_e32 v151, 0xffff0000, v105
	v_mul_f32_e32 v148, 0xbfb8aa3b, v148
	v_mul_f32_e32 v149, 0xbfb8aa3b, v149
	v_mul_f32_e32 v150, 0xbfb8aa3b, v150
	v_mul_f32_e32 v151, 0xbfb8aa3b, v151
	v_exp_f32_e32 v148, v148
	v_exp_f32_e32 v149, v149
	v_exp_f32_e32 v150, v150
	v_exp_f32_e32 v151, v151
	v_add_f32_e32 v148, 1.0, v148
	v_add_f32_e32 v149, 1.0, v149
	v_add_f32_e32 v150, 1.0, v150
	v_add_f32_e32 v151, 1.0, v151
	v_rcp_f32_e32 v148, v148
	v_rcp_f32_e32 v149, v149
	v_rcp_f32_e32 v150, v150
	v_rcp_f32_e32 v151, v151
	v_lshlrev_b32_e32 v104, 16, v100
	v_and_b32_e32 v105, 0xffff0000, v100
	v_lshlrev_b32_e32 v100, 16, v101
	v_and_b32_e32 v101, 0xffff0000, v101
	v_pk_fma_f32 v[34:35], v[34:35], v[148:149], v[104:105]
	v_pk_fma_f32 v[36:37], v[36:37], v[150:151], v[100:101]
	v_cvt_pk_bf16_f32 v102, v38, v39
	v_cvt_pk_bf16_f32 v103, v40, v41
	v_cvt_pk_bf16_f32 v104, v34, v35
	v_cvt_pk_bf16_f32 v105, v36, v37
	global_store_dwordx4 v[158:159], v[102:105], off offset:256
	s_mov_b64 s[4:5], 0x8000
	v_lshl_add_u64 v[158:159], v[158:159], 0, s[4:5]
	s_waitcnt vmcnt(13)
; __device__ __forceinline__ float bflo(unsigned w) { return __uint_as_float(w << 16); }
; __device__ __forceinline__ float bfhi(unsigned w) { return __uint_as_float(w & 0xffff0000u); }
; __device__ __forceinline__ unsigned pk2(float lo, float hi) { f32x2 v = {lo, hi}; bf16x2_t b = __builtin_convertvector(v, bf16x2_t); return __builtin_bit_cast(unsigned, b); }
;     template <int QPR> __device__ __forceinline__ void tailq(int row, int c, const f32x4 v, int) const { quad(row, c, v); }
; __device__ __forceinline__ float sigm(float x) { return __builtin_amdgcn_rcpf(1.f + __expf(-x)); }
;     __device__ __forceinline__ void quad(int row, int c, const f32x4 a) const {
;         const u32x2 gw = *(const u32x2*)(Z + (size_t)row * NZ + ZC_MB + c);
;         const u32x2 tw = *(const u32x2*)(T + (size_t)row * D + c); const f32x4 t = {bflo(tw.x), bfhi(tw.x), bflo(tw.y), bfhi(tw.y)};
;         const float v0 = t[0] + a[0] * sigm(bflo(gw.x)), v1 = t[1] + a[1] * sigm(bfhi(gw.x)), v2 = t[2] + a[2] * sigm(bflo(gw.y)), v3 = t[3] + a[3] * sigm(bfhi(gw.y));
;         u32x2 w; w.x = pk2(v0, v1); w.y = pk2(v2, v3);
;         *(u32x2*)(MG + (size_t)row * D + c) = w; }
;     template <int QPR> __device__ __forceinline__ void tailq(int row, int c, const f32x4 v, int) const { quad(row, c, v); }
;     __device__ __forceinline__ void operator()(const f32x4 (&acc)[2][2][4][2], const pg8::Unit& u, int wr, int wc, int fr, int fq) const {
;         const int row0 = u.pm * 256 + wr * 64 + fr, col0 = u.pn * 256 + wc * 32 + 4 * fq;
; #pragma unroll
;         for (int ai = 0; ai < 2; ++ai)
; #pragma unroll
;             for (int m = 0; m < 4; ++m) { const int row = row0 + ai * 128 + m * 16;
; #pragma unroll
;                 for (int bj = 0; bj < 2; ++bj)
; #pragma unroll
;                     for (int n = 0; n < 2; ++n) { const int c = col0 + bj * 128 + n * 16;
;                         quad(row, c, acc[ai][bj][m][n]); } }
	v_lshlrev_b32_e32 v148, 16, v94
	v_and_b32_e32 v149, 0xffff0000, v94
	v_lshlrev_b32_e32 v150, 16, v95
	v_and_b32_e32 v151, 0xffff0000, v95
	v_mul_f32_e32 v148, 0xbfb8aa3b, v148
	v_mul_f32_e32 v149, 0xbfb8aa3b, v149
	v_mul_f32_e32 v150, 0xbfb8aa3b, v150
	v_mul_f32_e32 v151, 0xbfb8aa3b, v151
	v_exp_f32_e32 v148, v148
	v_exp_f32_e32 v149, v149
	v_exp_f32_e32 v150, v150
	v_exp_f32_e32 v151, v151
	v_add_f32_e32 v148, 1.0, v148
	v_add_f32_e32 v149, 1.0, v149
	v_add_f32_e32 v150, 1.0, v150
	v_add_f32_e32 v151, 1.0, v151
	v_rcp_f32_e32 v148, v148
	v_rcp_f32_e32 v149, v149
	v_rcp_f32_e32 v150, v150
	v_rcp_f32_e32 v151, v151
	v_lshlrev_b32_e32 v94, 16, v90
	v_and_b32_e32 v95, 0xffff0000, v90
	v_lshlrev_b32_e32 v90, 16, v91
	v_and_b32_e32 v91, 0xffff0000, v91
	v_pk_fma_f32 v[30:31], v[30:31], v[148:149], v[94:95]
	v_pk_fma_f32 v[32:33], v[32:33], v[150:151], v[90:91]
	v_lshlrev_b32_e32 v148, 16, v96
	v_and_b32_e32 v149, 0xffff0000, v96
	v_lshlrev_b32_e32 v150, 16, v97
	v_and_b32_e32 v151, 0xffff0000, v97
	v_mul_f32_e32 v148, 0xbfb8aa3b, v148
	v_mul_f32_e32 v149, 0xbfb8aa3b, v149
	v_mul_f32_e32 v150, 0xbfb8aa3b, v150
	v_mul_f32_e32 v151, 0xbfb8aa3b, v151
	v_exp_f32_e32 v148, v148
	v_exp_f32_e32 v149, v149
	v_exp_f32_e32 v150, v150
	v_exp_f32_e32 v151, v151
	v_add_f32_e32 v148, 1.0, v148
	v_add_f32_e32 v149, 1.0, v149
	v_add_f32_e32 v150, 1.0, v150
	v_add_f32_e32 v151, 1.0, v151
	v_rcp_f32_e32 v148, v148
	v_rcp_f32_e32 v149, v149
	v_rcp_f32_e32 v150, v150
	v_rcp_f32_e32 v151, v151
	v_lshlrev_b32_e32 v96, 16, v92
	v_and_b32_e32 v97, 0xffff0000, v92
	v_lshlrev_b32_e32 v92, 16, v93
	v_and_b32_e32 v93, 0xffff0000, v93
	v_pk_fma_f32 v[26:27], v[26:27], v[148:149], v[96:97]
	v_pk_fma_f32 v[28:29], v[28:29], v[150:151], v[92:93]
	v_cvt_pk_bf16_f32 v94, v30, v31
	v_cvt_pk_bf16_f32 v95, v32, v33
	v_cvt_pk_bf16_f32 v96, v26, v27
	v_cvt_pk_bf16_f32 v97, v28, v29
	global_store_dwordx4 v[158:159], v[94:97], off
	s_waitcnt vmcnt(11)
	v_lshlrev_b32_e32 v148, 16, v86
	v_and_b32_e32 v149, 0xffff0000, v86
	v_lshlrev_b32_e32 v150, 16, v87
	v_and_b32_e32 v151, 0xffff0000, v87
	v_mul_f32_e32 v148, 0xbfb8aa3b, v148
	v_mul_f32_e32 v149, 0xbfb8aa3b, v149
	v_mul_f32_e32 v150, 0xbfb8aa3b, v150
	v_mul_f32_e32 v151, 0xbfb8aa3b, v151
	v_exp_f32_e32 v148, v148
	v_exp_f32_e32 v149, v149
	v_exp_f32_e32 v150, v150
	v_exp_f32_e32 v151, v151
	v_add_f32_e32 v148, 1.0, v148
	v_add_f32_e32 v149, 1.0, v149
	v_add_f32_e32 v150, 1.0, v150
	v_add_f32_e32 v151, 1.0, v151
	v_rcp_f32_e32 v148, v148
	v_rcp_f32_e32 v149, v149
	v_rcp_f32_e32 v150, v150
	v_rcp_f32_e32 v151, v151
	v_lshlrev_b32_e32 v86, 16, v82
	v_and_b32_e32 v87, 0xffff0000, v82
	v_lshlrev_b32_e32 v82, 16, v83
	v_and_b32_e32 v83, 0xffff0000, v83
	v_pk_fma_f32 v[22:23], v[22:23], v[148:149], v[86:87]
	v_pk_fma_f32 v[24:25], v[24:25], v[150:151], v[82:83]
	v_lshlrev_b32_e32 v148, 16, v88
	v_and_b32_e32 v149, 0xffff0000, v88
	v_lshlrev_b32_e32 v150, 16, v89
	v_and_b32_e32 v151, 0xffff0000, v89
	v_mul_f32_e32 v148, 0xbfb8aa3b, v148
	v_mul_f32_e32 v149, 0xbfb8aa3b, v149
	v_mul_f32_e32 v150, 0xbfb8aa3b, v150
	v_mul_f32_e32 v151, 0xbfb8aa3b, v151
	v_exp_f32_e32 v148, v148
	v_exp_f32_e32 v149, v149
	v_exp_f32_e32 v150, v150
	v_exp_f32_e32 v151, v151
	v_add_f32_e32 v148, 1.0, v148
	v_add_f32_e32 v149, 1.0, v149
	v_add_f32_e32 v150, 1.0, v150
	v_add_f32_e32 v151, 1.0, v151
	v_rcp_f32_e32 v148, v148
	v_rcp_f32_e32 v149, v149
	v_rcp_f32_e32 v150, v150
	v_rcp_f32_e32 v151, v151
	v_lshlrev_b32_e32 v88, 16, v84
	v_and_b32_e32 v89, 0xffff0000, v84
	v_lshlrev_b32_e32 v84, 16, v85
	v_and_b32_e32 v85, 0xffff0000, v85
	v_pk_fma_f32 v[18:19], v[18:19], v[148:149], v[88:89]
	v_pk_fma_f32 v[20:21], v[20:21], v[150:151], v[84:85]
	v_cvt_pk_bf16_f32 v86, v22, v23
	v_cvt_pk_bf16_f32 v87, v24, v25
	v_cvt_pk_bf16_f32 v88, v18, v19
	v_cvt_pk_bf16_f32 v89, v20, v21
	global_store_dwordx4 v[158:159], v[86:89], off offset:256
	s_mov_b64 s[4:5], 0x8000
	v_lshl_add_u64 v[158:159], v[158:159], 0, s[4:5]
	s_waitcnt vmcnt(9)
; __device__ __forceinline__ float bflo(unsigned w) { return __uint_as_float(w << 16); }
; __device__ __forceinline__ float bfhi(unsigned w) { return __uint_as_float(w & 0xffff0000u); }
; __device__ __forceinline__ unsigned pk2(float lo, float hi) { f32x2 v = {lo, hi}; bf16x2_t b = __builtin_convertvector(v, bf16x2_t); return __builtin_bit_cast(unsigned, b); }
; #define PG8_BAR __builtin_amdgcn_s_barrier()
; template <class Epi>
; __device__ __forceinline__ void gemm_phase(LAS unsigned char* lds, const Gemm g, const StaticOrder& S, const Epi& E) {
;     ...
;         if (wr == 0) PG8_BAR;
;         E(acc, cur, wr, wc, fr, fq);
;         if (!has_next) break;
; #pragma unroll
;         for (int a = 0; a < 2; ++a)
; #pragma unroll
;             for (int b = 0; b < 2; ++b)
; #pragma unroll
;                 for (int m = 0; m < 4; ++m)
; #pragma unroll
;                     for (int n = 0; n < 2; ++n) acc[a][b][m][n] = (f32x4){0.f, 0.f, 0.f, 0.f};
;         cur = nxt; cA = nA; cB = nB; ++ui;
;         if (wr == 1) PG8_BAR;
;     __device__ __forceinline__ void quad(int row, int c, const f32x4 a) const {
;         const u32x2 gw = *(const u32x2*)(Z + (size_t)row * NZ + ZC_MB + c);
;         const u32x2 tw = *(const u32x2*)(T + (size_t)row * D + c); const f32x4 t = {bflo(tw.x), bfhi(tw.x), bflo(tw.y), bfhi(tw.y)};
;         const float v0 = t[0] + a[0] * sigm(bflo(gw.x)), v1 = t[1] + a[1] * sigm(bfhi(gw.x)), v2 = t[2] + a[2] * sigm(bflo(gw.y)), v3 = t[3] + a[3] * sigm(bfhi(gw.y));
;         u32x2 w; w.x = pk2(v0, v1); w.y = pk2(v2, v3);
;         *(u32x2*)(MG + (size_t)row * D + c) = w; }
;     template <int QPR> __device__ __forceinline__ void tailq(int row, int c, const f32x4 v, int) const { quad(row, c, v); }
;     __device__ __forceinline__ void operator()(const f32x4 (&acc)[2][2][4][2], const pg8::Unit& u, int wr, int wc, int fr, int fq) const {
;         const int row0 = u.pm * 256 + wr * 64 + fr, col0 = u.pn * 256 + wc * 32 + 4 * fq;
; #pragma unroll
;         for (int ai = 0; ai < 2; ++ai)
; #pragma unroll
;             for (int m = 0; m < 4; ++m) { const int row = row0 + ai * 128 + m * 16;
; #pragma unroll
;                 for (int bj = 0; bj < 2; ++bj)
; #pragma unroll
;                     for (int n = 0; n < 2; ++n) { const int c = col0 + bj * 128 + n * 16;
;                         quad(row, c, acc[ai][bj][m][n]); } }
;     }
	v_lshlrev_b32_e32 v148, 16, v78
	v_and_b32_e32 v149, 0xffff0000, v78
	v_lshlrev_b32_e32 v150, 16, v79
	v_and_b32_e32 v151, 0xffff0000, v79
	v_mul_f32_e32 v148, 0xbfb8aa3b, v148
	v_mul_f32_e32 v149, 0xbfb8aa3b, v149
	v_mul_f32_e32 v150, 0xbfb8aa3b, v150
	v_mul_f32_e32 v151, 0xbfb8aa3b, v151
	v_exp_f32_e32 v148, v148
	v_exp_f32_e32 v149, v149
	v_exp_f32_e32 v150, v150
	v_exp_f32_e32 v151, v151
	v_add_f32_e32 v148, 1.0, v148
	v_add_f32_e32 v149, 1.0, v149
	v_add_f32_e32 v150, 1.0, v150
	v_add_f32_e32 v151, 1.0, v151
	v_rcp_f32_e32 v148, v148
	v_rcp_f32_e32 v149, v149
	v_rcp_f32_e32 v150, v150
	v_rcp_f32_e32 v151, v151
	v_lshlrev_b32_e32 v78, 16, v74
	v_and_b32_e32 v79, 0xffff0000, v74
	v_lshlrev_b32_e32 v74, 16, v75
	v_and_b32_e32 v75, 0xffff0000, v75
	v_pk_fma_f32 v[14:15], v[14:15], v[148:149], v[78:79]
	v_pk_fma_f32 v[16:17], v[16:17], v[150:151], v[74:75]
	v_lshlrev_b32_e32 v148, 16, v80
	v_and_b32_e32 v149, 0xffff0000, v80
	v_lshlrev_b32_e32 v150, 16, v81
	v_and_b32_e32 v151, 0xffff0000, v81
	v_mul_f32_e32 v148, 0xbfb8aa3b, v148
	v_mul_f32_e32 v149, 0xbfb8aa3b, v149
	v_mul_f32_e32 v150, 0xbfb8aa3b, v150
	v_mul_f32_e32 v151, 0xbfb8aa3b, v151
	v_exp_f32_e32 v148, v148
	v_exp_f32_e32 v149, v149
	v_exp_f32_e32 v150, v150
	v_exp_f32_e32 v151, v151
	v_add_f32_e32 v148, 1.0, v148
	v_add_f32_e32 v149, 1.0, v149
	v_add_f32_e32 v150, 1.0, v150
	v_add_f32_e32 v151, 1.0, v151
	v_rcp_f32_e32 v148, v148
	v_rcp_f32_e32 v149, v149
	v_rcp_f32_e32 v150, v150
	v_rcp_f32_e32 v151, v151
	v_lshlrev_b32_e32 v80, 16, v76
	v_and_b32_e32 v81, 0xffff0000, v76
	v_lshlrev_b32_e32 v76, 16, v77
	v_and_b32_e32 v77, 0xffff0000, v77
	v_pk_fma_f32 v[10:11], v[10:11], v[148:149], v[80:81]
	v_pk_fma_f32 v[12:13], v[12:13], v[150:151], v[76:77]
	v_cvt_pk_bf16_f32 v78, v14, v15
	v_cvt_pk_bf16_f32 v79, v16, v17
	v_cvt_pk_bf16_f32 v80, v10, v11
	v_cvt_pk_bf16_f32 v81, v12, v13
	global_store_dwordx4 v[158:159], v[78:81], off
	s_waitcnt vmcnt(7)
	v_lshlrev_b32_e32 v148, 16, v70
	v_and_b32_e32 v149, 0xffff0000, v70
	v_lshlrev_b32_e32 v150, 16, v71
	v_and_b32_e32 v151, 0xffff0000, v71
	v_mul_f32_e32 v148, 0xbfb8aa3b, v148
	v_mul_f32_e32 v149, 0xbfb8aa3b, v149
	v_mul_f32_e32 v150, 0xbfb8aa3b, v150
	v_mul_f32_e32 v151, 0xbfb8aa3b, v151
	v_exp_f32_e32 v148, v148
	v_exp_f32_e32 v149, v149
	v_exp_f32_e32 v150, v150
	v_exp_f32_e32 v151, v151
	v_add_f32_e32 v148, 1.0, v148
	v_add_f32_e32 v149, 1.0, v149
	v_add_f32_e32 v150, 1.0, v150
	v_add_f32_e32 v151, 1.0, v151
	v_rcp_f32_e32 v148, v148
	v_rcp_f32_e32 v149, v149
	v_rcp_f32_e32 v150, v150
	v_rcp_f32_e32 v151, v151
	v_lshlrev_b32_e32 v70, 16, v66
	v_and_b32_e32 v71, 0xffff0000, v66
	v_lshlrev_b32_e32 v66, 16, v67
	v_and_b32_e32 v67, 0xffff0000, v67
	v_pk_fma_f32 v[6:7], v[6:7], v[148:149], v[70:71]
	v_pk_fma_f32 v[8:9], v[8:9], v[150:151], v[66:67]
	v_lshlrev_b32_e32 v148, 16, v72
	v_and_b32_e32 v149, 0xffff0000, v72
	v_lshlrev_b32_e32 v150, 16, v73
	v_and_b32_e32 v151, 0xffff0000, v73
	v_mul_f32_e32 v148, 0xbfb8aa3b, v148
	v_mul_f32_e32 v149, 0xbfb8aa3b, v149
	v_mul_f32_e32 v150, 0xbfb8aa3b, v150
	v_mul_f32_e32 v151, 0xbfb8aa3b, v151
	v_exp_f32_e32 v148, v148
	v_exp_f32_e32 v149, v149
	v_exp_f32_e32 v150, v150
	v_exp_f32_e32 v151, v151
	v_add_f32_e32 v148, 1.0, v148
	v_add_f32_e32 v149, 1.0, v149
	v_add_f32_e32 v150, 1.0, v150
	v_add_f32_e32 v151, 1.0, v151
	v_rcp_f32_e32 v148, v148
	v_rcp_f32_e32 v149, v149
	v_rcp_f32_e32 v150, v150
	v_rcp_f32_e32 v151, v151
	v_lshlrev_b32_e32 v72, 16, v68
	v_and_b32_e32 v73, 0xffff0000, v68
	v_lshlrev_b32_e32 v68, 16, v69
	v_and_b32_e32 v69, 0xffff0000, v69
	v_pk_fma_f32 v[2:3], v[2:3], v[148:149], v[72:73]
	v_pk_fma_f32 v[4:5], v[4:5], v[150:151], v[68:69]
	v_cvt_pk_bf16_f32 v70, v6, v7
	v_cvt_pk_bf16_f32 v71, v8, v9
	v_cvt_pk_bf16_f32 v72, v2, v3
	v_cvt_pk_bf16_f32 v73, v4, v5
	global_store_dwordx4 v[158:159], v[70:73], off offset:256
	s_andn2_b64 vcc, exec, s[38:39]
	s_mov_b64 s[4:5], -1
	s_cbranch_vccnz .LBB0_782
	s_andn2_b64 vcc, exec, s[0:1]
	s_cbranch_vccnz .LBB0_781
	s_barrier
	s_branch .LBB0_781
